# grid barrier: XCD leader issues the XGEN release atomic before its own buffer_inv (was after)
# speedup vs baseline: 1.0044x; 1.0016x over previous
; __device__ __forceinline__ unsigned xb_add(unsigned* p, unsigned v) { return __hip_atomic_fetch_add(p, v, __ATOMIC_RELAXED, __HIP_MEMORY_SCOPE_AGENT); }
; __device__ __forceinline__ void xcd_barrier(const XcdBarrier& b, const int tid) {
;     ...
;             __builtin_amdgcn_fence(__ATOMIC_ACQUIRE, "agent");
;             xb_add(&bar[XB_XGEN(b.x)], 1u);
;             asm volatile("s_waitcnt vmcnt(0)" ::: "memory");
.LBB0_71:
	s_or_b64 exec, exec, s[4:5]
	s_mov_b64 s[4:5], exec
	v_mbcnt_lo_u32_b32 v1, s4, 0
	v_mbcnt_hi_u32_b32 v1, s5, v1
	v_cmp_eq_u32_e32 vcc, 0, v1
	s_waitcnt vmcnt(0)
	s_and_saveexec_b64 s[6:7], vcc
	s_cbranch_execz .LBB0_73
	s_bcnt1_i32_b64 s4, s[4:5]
	v_mov_b32_e32 v1, s4
	v_mov_b32_e32 v2, 0x2000
	global_atomic_add v2, v1, s[2:3] offset:1024
.LBB0_73:
	s_or_b64 exec, exec, s[6:7]
	buffer_inv sc1
	s_waitcnt vmcnt(0)
